# P1 section order variant: gate, attention q/k/v, ret q, ret k, ret v (ret q more recent for the retention block prologue)
# baseline (speedup 1.0000x reference)
; #define PG8_WAIT_V(n) asm volatile("s_waitcnt vmcnt(" #n ")" ::: "memory")
;     __host__ __device__ bool next(int i, Unit& u) const {
;         const long L = (long)i * G + c; if (L >= nwg) return false;
;         int wgid = (int)L; { const int q = nwg / NXCD, r = nwg % NXCD, xcd = wgid % NXCD, off = wgid / NXCD; wgid = (xcd < r ? xcd * (q + 1) : r * (q + 1) + (xcd - r) * q) + off; }
;         const int nig = wgm * nN, gid = wgid / nig, fm = gid * wgm, gsz = (nM - fm) < wgm ? (nM - fm) : wgm;
;         u.pm = fm + ((wgid % nig) % gsz); u.pn = (wgid % nig) / gsz; return true;
; template <class Epi, class Sched, bool ALIGN_EPI = false, bool SP2 = false>
; __device__ __forceinline__ void gemm_phase(PG8_LAS unsigned char* lds, const Gemm g, const Sched& S, const Epi& E) {
;     ...
;     const int tid = tid_, wid = __builtin_amdgcn_readfirstlane(tid >> 6), lane = tid & 63, wr = wid >> 2, wc = wid & 3, fr = lane & 15, fq = lane >> 4;
;     const int K = g.K, nt = K / BK;
;     unsigned voffA[2], voffB[2];
; #pragma unroll
;     for (int i = 0; i < 2; ++i) { int R, C; stage_rc(tid * 16 + i * 8192, R, C); const int Rb = Epi::PERM ? ((R & ~31) + perm32(R & 31)) : R;
;         voffA[i] = (unsigned)(R * K + C) * 2u; voffB[i] = (unsigned)(Rb * K + C) * 2u; }
;     const size_t kstep = (size_t)(BK * 2);
;     const size_t hstep = (size_t)HALF * K * 2;
;     const size_t tstep = 2 * hstep;
;     const unsigned ldsw = (unsigned)wid * 1024u;
;     const int aoff = lds_byte(wr * 64 + fr, fq * 8), boff = lds_byte(wc * 32 + fr, fq * 8);
;     ...
;     Unit cur, nxt; int ui = 0;
;     if (!S.next(0, cur)) return;
;     f32x4 acc[2][2][4][2];
; #pragma unroll
;     for (int a = 0; a < 2; ++a)
; #pragma unroll
;         for (int b = 0; b < 2; ++b)
; #pragma unroll
;             for (int m = 0; m < 4; ++m)
; #pragma unroll
;                 for (int n = 0; n < 2; ++n) acc[a][b][m][n] = (f32x4){0.f, 0.f, 0.f, 0.f};
;     bf16x8 At[4][2], B0[2][2], B1[2][2];
;     const char* cA = (const char*)g.A + (size_t)cur.pm * tstep; const char* cB = (const char*)g.Bt + (size_t)cur.pn * tstep;
;     S.a_ready(cur);
;     if constexpr (SP2) {
;         PG8_STAGE(PG8_SB(0, 0), cB, voffB); PG8_STAGE(PG8_SB(0, 1), cB + hstep, voffB); PG8_STAGE(PG8_SA(0, 0), cA, voffA); PG8_STAGE(PG8_SA(0, 1), cA + hstep, voffA);
;         if (wr == 1) PG8_BAR;
;         PG8_WAIT_V(2); PG8_BAR;
.LBB0_80:
	v_readlane_b32 s4, v244, 10
	v_readlane_b32 s5, v244, 11
	s_cmp_lt_i32 s4, 2
	s_cselect_b64 s[4:5], -1, 0
	s_add_u32 s6, s76, 0x1d00000
	s_addc_u32 s7, s77, 0
	v_writelane_b32 v244, s6, 29
	s_nop 1
	v_writelane_b32 v244, s7, 30
	s_add_u32 s6, s76, 0x2500000
	s_addc_u32 s7, s77, 0
	s_add_u32 s72, s76, 0x5100000
	s_addc_u32 s73, s77, 0
	s_add_u32 s60, s76, 0x6800000
	s_addc_u32 s61, s77, 0
	v_writelane_b32 v244, s6, 31
	s_add_u32 s84, s76, 0xa800000
	s_addc_u32 s85, s77, 0
	v_writelane_b32 v244, s7, 32
	s_and_b64 s[0:1], s[4:5], s[0:1]
	v_writelane_b32 v244, s0, 33
	s_andn2_b64 vcc, exec, s[0:1]
	s_nop 0
	v_writelane_b32 v244, s1, 34
	s_cbranch_vccnz .LBB0_154
	v_writelane_b32 v253, s4, 0
	v_writelane_b32 v253, s5, 1
	v_writelane_b32 v253, s6, 2
	v_writelane_b32 v253, s7, 3
	v_writelane_b32 v253, s8, 4
	v_writelane_b32 v253, s9, 5
	v_writelane_b32 v253, s10, 6
	v_writelane_b32 v253, s11, 7
	v_writelane_b32 v253, s12, 8
	v_writelane_b32 v253, s13, 9
	v_writelane_b32 v253, s14, 10
	v_writelane_b32 v253, s15, 11
	v_writelane_b32 v253, s16, 12
	v_writelane_b32 v253, s17, 13
	v_writelane_b32 v253, s18, 14
	v_writelane_b32 v253, s19, 15
	v_writelane_b32 v253, s20, 16
	v_writelane_b32 v253, s21, 17
	v_writelane_b32 v253, s22, 18
	v_writelane_b32 v253, s23, 19
	v_writelane_b32 v253, s24, 20
	v_writelane_b32 v253, s25, 21
	v_writelane_b32 v253, s26, 22
	v_writelane_b32 v253, s27, 23
	v_writelane_b32 v253, s28, 24
	v_writelane_b32 v253, s29, 25
	v_writelane_b32 v253, s30, 26
	v_writelane_b32 v253, s31, 27
	v_writelane_b32 v253, s32, 28
	v_writelane_b32 v253, s33, 29
	v_writelane_b32 v253, s34, 30
	v_writelane_b32 v253, s35, 31
	v_writelane_b32 v253, s36, 32
	v_writelane_b32 v253, s37, 33
	v_writelane_b32 v253, s38, 34
	v_writelane_b32 v253, s39, 35
	v_writelane_b32 v253, s40, 36
	v_writelane_b32 v253, s41, 37
	v_writelane_b32 v253, s42, 38
	v_writelane_b32 v253, s43, 39
	v_writelane_b32 v253, s44, 40
	v_writelane_b32 v253, s45, 41
	v_writelane_b32 v253, s46, 42
	v_writelane_b32 v253, s47, 43
	v_writelane_b32 v253, s48, 44
	v_writelane_b32 v253, s49, 45
	v_writelane_b32 v253, s50, 46
	v_writelane_b32 v253, s51, 47
	v_writelane_b32 v253, s52, 48
	v_writelane_b32 v253, s53, 49
	v_writelane_b32 v253, s54, 50
	v_writelane_b32 v253, s55, 51
	v_writelane_b32 v253, s56, 52
	v_writelane_b32 v253, s57, 53
	v_writelane_b32 v253, s58, 54
	v_writelane_b32 v253, s59, 55
	s_mov_b32 s40, vcc_lo
	s_mov_b32 s41, vcc_hi
	v_writelane_b32 v253, s40, 60
	v_writelane_b32 v253, s41, 61
	v_lshrrev_b32_e32 v254, 6, v185
	v_readlane_b32 s14, v244, 4
	v_readfirstlane_b32 s36, v254
	s_nop 3
	s_lshr_b32 s37, s36, 2
	s_and_b32 s38, s36, 3
	s_lshl_b32 s35, s36, 10
	s_add_u32 s10, s76, 0x6800000
	s_addc_u32 s11, s77, 0
	s_add_u32 s12, s76, 0x100000
	s_addc_u32 s13, s77, 0
	v_readlane_b32 s6, v244, 28
	s_lshl_b32 s7, s14, 3
	s_mov_b32 s16, 0
	s_mul_i32 s40, s16, s14
	s_add_u32 s40, s40, s2
	s_cmp_lt_u32 s40, 1792
	s_cselect_b32 s44, 1, 0
	s_min_u32 s40, s40, 1791
	s_and_b32 s41, s40, 7
	s_lshr_b32 s42, s40, 3
	s_mul_i32 s41, s41, 224
	s_add_u32 s41, s41, s42
	s_mul_hi_u32 s42, s41, 0x124924a
	s_mul_i32 s43, s42, 224
	s_sub_u32 s43, s41, s43
	s_and_b32 s40, s43, 7
	s_lshl_b32 s42, s42, 3
	s_add_u32 s17, s42, s40
	s_lshr_b32 s18, s43, 3
	s_lshr_b32 s40, s18, 2
	s_lshl_b32 s40, s40, 2
	s_lshr_b32 s41, 0x5432106, s40
	s_and_b32 s41, s41, 7
	s_and_b32 s18, s18, 3
	s_lshl_b32 s41, s41, 2
	s_or_b32 s18, s18, s41
	s_cmp_eq_u32 s44, 0
	s_cbranch_scc1 .Lp1_exit
	v_and_b32_e32 v254, 63, v185
	v_and_b32_e32 v255, 15, v254
	v_lshrrev_b32_e32 v186, 1, v255
	v_lshrrev_b32_e32 v187, 4, v254
	v_xor_b32_e32 v186, v186, v187
	v_lshlrev_b32_e32 v255, 7, v255
	v_lshl_or_b32 v255, v186, 4, v255
	s_lshl_b32 s40, s37, 13
	s_lshl_b32 s41, s38, 12
	s_add_u32 s41, s41, 0x10000
	v_add_u32_e32 v245, s40, v255
	v_add_u32_e32 v247, s41, v255
	v_xor_b32_e32 v246, 64, v245
	v_xor_b32_e32 v248, 64, v247
	v_lshrrev_b32_e32 v255, 3, v254
	v_and_b32_e32 v186, 7, v254
	s_and_b32 s40, s36, 1
	s_lshl_b32 s40, s40, 2
	v_lshrrev_b32_e32 v187, 1, v255
	v_add_u32_e32 v187, s40, v187
	v_xor_b32_e32 v186, v186, v187
	v_lshlrev_b32_e32 v186, 4, v186
	s_lshl_b32 s40, s36, 3
	v_add_u32_e32 v187, s40, v255
	v_mul_u32_u24_e32 v187, 0x1000, v187
	v_add_u32_e32 v249, v187, v186
	v_add_u32_e32 v250, 0x40000, v249
	s_and_b32 s40, s36, 3
	s_lshl_b32 s40, s40, 3
	v_add_u32_e32 v187, s40, v255
	v_lshrrev_b32_e32 v254, 4, v187
	v_lshlrev_b32_e32 v254, 2, v254
	v_and_b32_e32 v255, 3, v187
	v_add_u32_e32 v254, v254, v255
	v_and_b32_e32 v187, 12, v187
	v_lshl_add_u32 v254, v187, 1, v254
	s_lshr_b32 s40, s36, 2
	s_lshl_b32 s40, s40, 5
	v_add_u32_e32 v254, s40, v254
	v_mul_u32_u24_e32 v254, 0x1000, v254
	v_add_u32_e32 v251, v254, v186
	v_add_u32_e32 v252, 0x40000, v251
	s_mul_i32 s40, s17, 0x100000
	s_add_u32 s22, s10, s40
	s_addc_u32 s23, s11, 0
	s_mul_i32 s40, s18, 0x100000
	s_add_u32 s24, s12, s40
	s_addc_u32 s25, s13, 0
	s_and_b32 s40, s16, 1
	s_lshl_b32 s4, s40, 8
	s_sub_u32 s4, 128, s4
	s_sub_u32 s5, 0, s40
	s_mul_i32 s8, s40, 3968
	s_add_u32 s30, s22, s8
	s_addc_u32 s31, s23, 0
	s_add_u32 s32, s24, s8
	s_addc_u32 s33, s25, 0
	s_add_u32 s56, s30, 0x80000
	s_addc_u32 s57, s31, 0
	s_add_u32 s58, s32, 0x80000
	s_addc_u32 s59, s33, 0
	s_add_i32 m0, s35, 0x0
	s_nop 0
	global_load_lds_dwordx4 v249, s[30:31]
	s_add_i32 m0, s35, 0x2000
	s_nop 0
	global_load_lds_dwordx4 v250, s[30:31]
	s_add_i32 m0, s35, 0x10000
	s_nop 0
	global_load_lds_dwordx4 v251, s[32:33]
	s_add_i32 m0, s35, 0x12000
	s_nop 0
	global_load_lds_dwordx4 v252, s[32:33]
	s_add_i32 m0, s35, 0x4000
	s_nop 0
	global_load_lds_dwordx4 v249, s[56:57]
	s_add_i32 m0, s35, 0x6000
	s_nop 0
	global_load_lds_dwordx4 v250, s[56:57]
	s_add_i32 m0, s35, 0x14000
	s_nop 0
	global_load_lds_dwordx4 v251, s[58:59]
	s_add_i32 m0, s35, 0x16000
	s_nop 0
	global_load_lds_dwordx4 v252, s[58:59]
	s_add_u32 s30, s30, s4
	s_addc_u32 s31, s31, s5
	s_add_u32 s56, s56, s4
	s_addc_u32 s57, s57, s5
	s_add_u32 s32, s32, s4
	s_addc_u32 s33, s33, s5
	s_add_u32 s58, s58, s4
	s_addc_u32 s59, s59, s5
	s_add_i32 m0, s35, 0x8000
	s_nop 0
	global_load_lds_dwordx4 v249, s[30:31]
	s_add_i32 m0, s35, 0xa000
	s_nop 0
	global_load_lds_dwordx4 v250, s[30:31]
	s_add_i32 m0, s35, 0x1c000
	s_nop 0
	global_load_lds_dwordx4 v251, s[58:59]
	s_add_i32 m0, s35, 0x1e000
	s_nop 0
	global_load_lds_dwordx4 v252, s[58:59]
	s_add_i32 m0, s35, 0xc000
	s_nop 0
	global_load_lds_dwordx4 v249, s[56:57]
	s_add_i32 m0, s35, 0xe000
	s_nop 0
	global_load_lds_dwordx4 v250, s[56:57]
	s_add_i32 m0, s35, 0x18000
	s_nop 0
	global_load_lds_dwordx4 v251, s[32:33]
	s_add_i32 m0, s35, 0x1a000
	s_nop 0
	global_load_lds_dwordx4 v252, s[32:33]
	s_add_u32 s30, s30, s4
	s_addc_u32 s31, s31, s5
	s_add_u32 s56, s56, s4
	s_addc_u32 s57, s57, s5
	s_add_u32 s32, s32, s4
	s_addc_u32 s33, s33, s5
	s_add_u32 s58, s58, s4
	s_addc_u32 s59, s59, s5
	s_waitcnt vmcnt(12)
	s_barrier
; #define PG8_STAGE(bufoff, gbase, voff) do { _Pragma("unroll") for (int _i = 0; _i < 2; ++_i) \
;         __builtin_amdgcn_global_load_lds((const unsigned*)((const char*)(gbase) + (voff)[_i]), (PG8_LAS unsigned*)(lds + (bufoff) + ldsw + _i * 8192), 16, 0, 0); } while (0)
; #define PG8_LDA(dst, b, h) do { _Pragma("unroll") for (int m = 0; m < 4; ++m) _Pragma("unroll") for (int k = 0; k < 2; ++k) dst[m][k] = *(const PG8_LAS bf16x8*)(lds + PG8_SA(b, h) + aoff + m * 2048 + k * 1024); } while (0)
; #define PG8_LDB(dst, b, h) do { _Pragma("unroll") for (int n = 0; n < 2; ++n) _Pragma("unroll") for (int k = 0; k < 2; ++k) dst[n][k] = *(const PG8_LAS bf16x8*)(lds + PG8_SB(b, h) + boff + n * 2048 + k * 1024); } while (0)
; #define PG8_SCHED __builtin_amdgcn_sched_barrier(0)
;     __host__ __device__ bool next(int i, Unit& u) const {
;         const long L = (long)i * G + c; if (L >= nwg) return false;
;         int wgid = (int)L; { const int q = nwg / NXCD, r = nwg % NXCD, xcd = wgid % NXCD, off = wgid / NXCD; wgid = (xcd < r ? xcd * (q + 1) : r * (q + 1) + (xcd - r) * q) + off; }
;         const int nig = wgm * nN, gid = wgid / nig, fm = gid * wgm, gsz = (nM - fm) < wgm ? (nM - fm) : wgm;
;         u.pm = fm + ((wgid % nig) % gsz); u.pn = (wgid % nig) / gsz; return true;
; template <class Epi, class Sched, bool ALIGN_EPI = false, bool SP2 = false>
; __device__ __forceinline__ void gemm_phase(PG8_LAS unsigned char* lds, const Gemm g, const Sched& S, const Epi& E) {
;     ...
;     for (;;) {
;         const bool has_next = S.next(ui + 1, nxt);
;         const char* nA = has_next ? (const char*)g.A + (size_t)nxt.pm * tstep : cA; const char* nB = has_next ? (const char*)g.Bt + (size_t)nxt.pn * tstep : cB;
;         for (int t = 0; t < nt; t += 2) {
;             const bool last = (t == nt - 2);
;             const char* a1 = cA + (size_t)(t + 1) * kstep;
;             const char* a2 = last ? nA : cA + (size_t)(t + 2) * kstep; const char* b2 = last ? nB : cB + (size_t)(t + 2) * kstep;
;             const char* a3 = a2 + kstep; const char* b3 = b2 + kstep;
;             if (last && has_next) S.a_ready(nxt);
;             if constexpr (SP2) {
;             PG8_LDB(B0, 0, 0); PG8_LDB(B1, 0, 1); PG8_SCHED; PG8_LDA(At, 0, 0); PG8_STAGE(PG8_SA(1, 1), a1 + hstep, voffA);
.Lp1_unit:
	s_add_u32 s45, s16, 1
	s_mul_i32 s40, s45, s14
	s_add_u32 s40, s40, s2
	s_cmp_lt_u32 s40, 1792
	s_cselect_b32 s19, 1, 0
	s_min_u32 s40, s40, 1791
	s_and_b32 s41, s40, 7
	s_lshr_b32 s42, s40, 3
	s_mul_i32 s41, s41, 224
	s_add_u32 s41, s41, s42
	s_mul_hi_u32 s42, s41, 0x124924a
	s_mul_i32 s43, s42, 224
	s_sub_u32 s43, s41, s43
	s_and_b32 s40, s43, 7
	s_lshl_b32 s42, s42, 3
	s_add_u32 s20, s42, s40
	s_lshr_b32 s21, s43, 3
	s_lshr_b32 s40, s21, 2
	s_lshl_b32 s40, s40, 2
	s_lshr_b32 s41, 0x5432106, s40
	s_and_b32 s41, s41, 7
	s_and_b32 s21, s21, 3
	s_lshl_b32 s41, s41, 2
	s_or_b32 s21, s21, s41
	s_mul_i32 s40, s20, 0x100000
	s_add_u32 s26, s10, s40
	s_addc_u32 s27, s11, 0
	s_mul_i32 s40, s21, 0x100000
	s_add_u32 s28, s12, s40
	s_addc_u32 s29, s13, 0
	s_cmp_eq_u32 s19, 0
	s_cselect_b32 s26, s22, s26
	s_cselect_b32 s27, s23, s27
	s_cselect_b32 s28, s24, s28
	s_cselect_b32 s29, s25, s29
	s_add_u32 s30, s22, s8
	s_addc_u32 s31, s23, 0
	s_add_u32 s32, s24, s8
	s_addc_u32 s33, s25, 0
	s_add_u32 s30, s30, s4
	s_addc_u32 s31, s31, s5
	s_add_u32 s32, s32, s4
	s_addc_u32 s33, s33, s5
	s_add_u32 s30, s30, s4
	s_addc_u32 s31, s31, s5
	s_add_u32 s32, s32, s4
	s_addc_u32 s33, s33, s5
	s_add_u32 s56, s30, 0x80000
	s_addc_u32 s57, s31, 0
	s_add_u32 s58, s32, 0x80000
	s_addc_u32 s59, s33, 0
	s_movk_i32 s34, 16
	v_mov_b32_e32 v0, 0
	v_mov_b32_e32 v1, 0
	v_mov_b32_e32 v2, 0
	v_mov_b32_e32 v3, 0
	v_mov_b32_e32 v4, 0
	v_mov_b32_e32 v5, 0
	v_mov_b32_e32 v6, 0
	v_mov_b32_e32 v7, 0
	v_mov_b32_e32 v8, 0
	v_mov_b32_e32 v9, 0
	v_mov_b32_e32 v10, 0
	v_mov_b32_e32 v11, 0
	v_mov_b32_e32 v12, 0
	v_mov_b32_e32 v13, 0
	v_mov_b32_e32 v14, 0
	v_mov_b32_e32 v15, 0
	v_mov_b32_e32 v16, 0
	v_mov_b32_e32 v17, 0
	v_mov_b32_e32 v18, 0
	v_mov_b32_e32 v19, 0
	v_mov_b32_e32 v20, 0
	v_mov_b32_e32 v21, 0
	v_mov_b32_e32 v22, 0
	v_mov_b32_e32 v23, 0
	v_mov_b32_e32 v24, 0
	v_mov_b32_e32 v25, 0
	v_mov_b32_e32 v26, 0
	v_mov_b32_e32 v27, 0
	v_mov_b32_e32 v28, 0
	v_mov_b32_e32 v29, 0
	v_mov_b32_e32 v30, 0
	v_mov_b32_e32 v31, 0
	v_mov_b32_e32 v32, 0
	v_mov_b32_e32 v33, 0
	v_mov_b32_e32 v34, 0
	v_mov_b32_e32 v35, 0
	v_mov_b32_e32 v36, 0
	v_mov_b32_e32 v37, 0
	v_mov_b32_e32 v38, 0
	v_mov_b32_e32 v39, 0
	v_mov_b32_e32 v40, 0
	v_mov_b32_e32 v41, 0
	v_mov_b32_e32 v42, 0
	v_mov_b32_e32 v43, 0
	v_mov_b32_e32 v44, 0
	v_mov_b32_e32 v45, 0
	v_mov_b32_e32 v46, 0
	v_mov_b32_e32 v47, 0
	v_mov_b32_e32 v48, 0
	v_mov_b32_e32 v49, 0
	v_mov_b32_e32 v50, 0
	v_mov_b32_e32 v51, 0
	v_mov_b32_e32 v52, 0
	v_mov_b32_e32 v53, 0
	v_mov_b32_e32 v54, 0
	v_mov_b32_e32 v55, 0
	v_mov_b32_e32 v56, 0
	v_mov_b32_e32 v57, 0
	v_mov_b32_e32 v58, 0
	v_mov_b32_e32 v59, 0
	v_mov_b32_e32 v60, 0
	v_mov_b32_e32 v61, 0
	v_mov_b32_e32 v62, 0
	v_mov_b32_e32 v63, 0
	v_mov_b32_e32 v64, 0
	v_mov_b32_e32 v65, 0
	v_mov_b32_e32 v66, 0
	v_mov_b32_e32 v67, 0
	v_mov_b32_e32 v68, 0
	v_mov_b32_e32 v69, 0
	v_mov_b32_e32 v70, 0
	v_mov_b32_e32 v71, 0
	v_mov_b32_e32 v72, 0
	v_mov_b32_e32 v73, 0
	v_mov_b32_e32 v74, 0
	v_mov_b32_e32 v75, 0
	v_mov_b32_e32 v76, 0
	v_mov_b32_e32 v77, 0
	v_mov_b32_e32 v78, 0
	v_mov_b32_e32 v79, 0
	v_mov_b32_e32 v80, 0
	v_mov_b32_e32 v81, 0
	v_mov_b32_e32 v82, 0
	v_mov_b32_e32 v83, 0
	v_mov_b32_e32 v84, 0
	v_mov_b32_e32 v85, 0
	v_mov_b32_e32 v86, 0
	v_mov_b32_e32 v87, 0
	v_mov_b32_e32 v88, 0
	v_mov_b32_e32 v89, 0
	v_mov_b32_e32 v90, 0
	v_mov_b32_e32 v91, 0
	v_mov_b32_e32 v92, 0
	v_mov_b32_e32 v93, 0
	v_mov_b32_e32 v94, 0
	v_mov_b32_e32 v95, 0
	v_mov_b32_e32 v96, 0
	v_mov_b32_e32 v97, 0
	v_mov_b32_e32 v98, 0
	v_mov_b32_e32 v99, 0
	v_mov_b32_e32 v100, 0
	v_mov_b32_e32 v101, 0
	v_mov_b32_e32 v102, 0
	v_mov_b32_e32 v103, 0
	v_mov_b32_e32 v104, 0
	v_mov_b32_e32 v105, 0
	v_mov_b32_e32 v106, 0
	v_mov_b32_e32 v107, 0
	v_mov_b32_e32 v108, 0
	v_mov_b32_e32 v109, 0
	v_mov_b32_e32 v110, 0
	v_mov_b32_e32 v111, 0
	v_mov_b32_e32 v112, 0
	v_mov_b32_e32 v113, 0
	v_mov_b32_e32 v114, 0
	v_mov_b32_e32 v115, 0
	v_mov_b32_e32 v116, 0
	v_mov_b32_e32 v117, 0
	v_mov_b32_e32 v118, 0
	v_mov_b32_e32 v119, 0
	v_mov_b32_e32 v120, 0
	v_mov_b32_e32 v121, 0
	v_mov_b32_e32 v122, 0
	v_mov_b32_e32 v123, 0
	v_mov_b32_e32 v124, 0
	v_mov_b32_e32 v125, 0
	v_mov_b32_e32 v126, 0
	v_mov_b32_e32 v127, 0
	ds_read_b128 v[196:199], v247 offset:0
	ds_read_b128 v[200:203], v248 offset:0
	ds_read_b128 v[204:207], v247 offset:2048
	ds_read_b128 v[208:211], v248 offset:2048
	ds_read_b128 v[128:131], v245 offset:0
	ds_read_b128 v[132:135], v246 offset:0
	ds_read_b128 v[136:139], v245 offset:2048
	ds_read_b128 v[140:143], v246 offset:2048
	ds_read_b128 v[144:147], v245 offset:4096
	ds_read_b128 v[148:151], v246 offset:4096
	ds_read_b128 v[152:155], v245 offset:6144
	ds_read_b128 v[156:159], v246 offset:6144
	s_cmp_ge_u32 s36, 4
	s_cbranch_scc1 .Lp1_kloop1
